# MLA loop: dropped the redundant vmcnt(0) between the two K chunk loads and moved the per-tile barriers below the next tile's global-load issue
# speedup vs baseline: 1.0290x; 1.0020x over previous
; template <bool MLA, int DK, int DV>
; __device__ __forceinline__ void attn_core(const Params& p, int b, int h, int map, int q0, int nt, char* smem,
;                                           f32x16 (&o)[DV / 32], float& lout) {
;     ...
;     __syncthreads();
;   };
;   for (int kt = 0; kt < nt; kt += 2) {
;     step(kt, sc_cur, sc_nxt);
;     step(kt + 1, sc_nxt, sc_cur);
;   }
.LBB0_542:
	s_or_b64 exec, exec, s[16:17]
	s_add_i32 s68, s68, 2
	v_add_u32_e32 v158, 0x80, v158
	v_add_u32_e32 v154, 0x80, v154
	s_cmp_lt_u32 s78, s34
	v_lshl_add_u64 v[150:151], v[150:151], 0, s[4:5]
	s_waitcnt lgkmcnt(0)
	s_cbranch_scc0 .LBB0_605

.LBB0_550:
	s_or_b64 exec, exec, s[16:17]
	s_and_saveexec_b64 s[16:17], s[8:9]
	s_cbranch_execz .LBB0_556
	v_add_u32_e32 v128, s38, v154
	v_add_u32_e32 v130, 0x80, v128
	v_ashrrev_i32_e32 v131, 31, v130
	s_and_saveexec_b64 s[72:73], s[14:15]
	s_xor_b64 s[72:73], exec, s[72:73]
	v_lshlrev_b64 v[128:129], 6, v[130:131]
	s_movk_i32 s60, 0xff80
	v_lshl_add_u64 v[128:129], v[144:145], 0, v[128:129]
	s_mov_b32 s61, -1
	v_lshl_add_u64 v[128:129], v[128:129], 0, s[60:61]
	s_andn2_saveexec_b64 s[72:73], s[72:73]
	v_mad_i64_i32 v[128:129], s[74:75], v130, s1, v[146:147]
	s_or_b64 exec, exec, s[72:73]
	global_load_dwordx4 v[128:131], v[128:129], off

; template <bool MLA, int DK, int DV>
; __device__ __forceinline__ void attn_core(const Params& p, int b, int h, int map, int q0, int nt, char* smem,
;                                           f32x16 (&o)[DV / 32], float& lout) {
;     ...
;         for (int i = 0; i < 16; ++i) nxt_[sub][i] = 0.f;
;       constexpr int NM = 2 * NKS;
;       bf16x8 kf[NM];
; #pragma unroll
;       for (int j = 0; j < NM; ++j) kf[j] = *(const bf16x8*)(Kn + ((j / NKS) * 32 + r) * KS_STRIDE + (j % NKS) * 16 + h2 * 8);
; #pragma unroll
;       for (int j = 0; j < NM; ++j) {
;         nxt_[j / NKS] = MFMA32(kf[j], qf[j % NKS], nxt_[j / NKS]);
; #pragma unroll
;         for (int e_ = j * 32 / NM; e_ < (j + 1) * 32 / NM; ++e_) {
;           const float x_ = __builtin_amdgcn_exp2f(fmaf(cur_[e_ >> 4][e_ & 15], sc, -mrun));
;           cur_[e_ >> 4][e_ & 15] = x_; psum += x_;
;         }
;       }
;       __builtin_amdgcn_sched_group_barrier(0x100, NM, 0);
; #pragma unroll
;       for (int j = 0; j < NM; ++j) {
;         __builtin_amdgcn_sched_group_barrier(0x008, 1, 0);
;         __builtin_amdgcn_sched_group_barrier(0x002, 96 / NM, 0);
;       }
;     } else {
; #pragma unroll
;       for (int sub = 0; sub < 2; ++sub)
; #pragma unroll
;         for (int i = 0; i < 16; ++i) { const float x_ = __builtin_amdgcn_exp2f(fmaf(cur_[sub][i], sc, -mrun)); cur_[sub][i] = x_; psum += x_; }
;     }
;     lrun += psum;
;     bf16x8 pb[4];
; #pragma unroll
;     for (int kb = 0; kb < 4; ++kb) {
;       const int sub = kb >> 1, s8 = (kb & 1) * 8;
;       u32x4 pk;
;       pk.x = pack2(cur_[sub][s8 + 0], cur_[sub][s8 + 1]);
;       pk.y = pack2(cur_[sub][s8 + 2], cur_[sub][s8 + 3]);
;       pk.z = pack2(cur_[sub][s8 + 4], cur_[sub][s8 + 5]);
;       pk.w = pack2(cur_[sub][s8 + 6], cur_[sub][s8 + 7]);
;       pb[kb] = __builtin_bit_cast(bf16x8, pk);
;     }
;     float mx = -INFINITY;
; #pragma unroll
;     for (int hb = 0; hb < 2; ++hb) {
;       bf16x8 vf[2][NDVT];
; #pragma unroll
;       for (int q = 0; q < 2; ++q)
; #pragma unroll
;         for (int d = 0; d < NDVT; ++d) {
;           const bft* vp = Vc + (d * 32 + r) * VS_STRIDE + (hb * 2 + q) * 16 + 4 * h2;
;           const u32x2 lo = *(const u32x2*)vp, hi = *(const u32x2*)(vp + 8);
;           const u32x4 pa4 = {lo.x, lo.y, hi.x, hi.y};
;           vf[q][d] = __builtin_bit_cast(bf16x8, pa4);
;         }
; #pragma unroll
.LBB0_559:
	s_or_b64 exec, exec, s[74:75]
	s_barrier
	s_and_b64 vcc, exec, s[76:77]
	s_cbranch_vccnz .Lmla1_cold
	ds_read_b128 v[132:135], v155 offset:13312
	ds_read_b128 v[136:139], v155 offset:13344
	ds_read_b128 v[198:201], v155 offset:13376
	ds_read_b128 v[202:205], v155 offset:13408
	ds_read_b128 v[248:251], v155 offset:13440
	ds_read_b128 v[216:219], v155 offset:13472
	ds_read_b128 v[220:223], v155 offset:19968
	ds_read_b128 v[224:227], v155 offset:20000
	ds_read_b128 v[228:231], v155 offset:20032
	ds_read_b128 v[232:235], v155 offset:20064
	ds_read_b128 v[236:239], v155 offset:20096
	ds_read_b128 v[240:243], v155 offset:20128
	v_add_u32_e32 v244, 0x6800, v157
	v_add_u32_e32 v245, 0x7800, v157
	v_exp_f32_e32 v16, v16
	v_exp_f32_e32 v17, v17
	v_exp_f32_e32 v18, v18
	v_exp_f32_e32 v19, v19
	v_add_f32_e32 v163, v16, v18
	v_add_f32_e32 v210, v17, v19
	s_waitcnt lgkmcnt(11)
	v_mfma_f32_32x32x16_bf16 v[48:63], v[132:135], v[96:99], v[164:179]
	v_exp_f32_e32 v20, v20
	v_exp_f32_e32 v21, v21
	v_exp_f32_e32 v22, v22
	s_waitcnt lgkmcnt(10)
	v_mfma_f32_32x32x16_bf16 v[48:63], v[136:139], v[100:103], v[48:63]
	v_exp_f32_e32 v23, v23
	v_add_f32_e32 v163, v20, v163
	v_add_f32_e32 v210, v21, v210
	s_waitcnt lgkmcnt(9)
	v_mfma_f32_32x32x16_bf16 v[48:63], v[198:201], v[104:107], v[48:63]
	v_add_f32_e32 v163, v22, v163
	v_add_f32_e32 v210, v23, v210
	v_cvt_pk_bf16_f32 v180, v16, v17
	v_cvt_pk_bf16_f32 v181, v18, v19
	v_cvt_pk_bf16_f32 v182, v20, v21
	s_waitcnt lgkmcnt(8)
	v_mfma_f32_32x32x16_bf16 v[48:63], v[202:205], v[108:111], v[48:63]
	v_cvt_pk_bf16_f32 v183, v22, v23
	v_exp_f32_e32 v24, v24
	v_exp_f32_e32 v25, v25
	s_waitcnt lgkmcnt(7)
	v_mfma_f32_32x32x16_bf16 v[48:63], v[248:251], v[112:115], v[48:63]
	v_exp_f32_e32 v26, v26
	v_exp_f32_e32 v27, v27
	v_add_f32_e32 v163, v24, v163
	s_waitcnt lgkmcnt(6)
	v_mfma_f32_32x32x16_bf16 v[48:63], v[216:219], v[116:119], v[48:63]
	ds_read2_b64 v[132:135], v244 offset0:0 offset1:2
	ds_read2_b64 v[136:139], v245 offset0:32 offset1:34
	ds_read2_b64 v[198:201], v244 offset0:4 offset1:6
	ds_read2_b64 v[202:205], v245 offset0:36 offset1:38
	ds_read2_b64 v[248:251], v244 offset0:8 offset1:10
	ds_read2_b64 v[216:219], v245 offset0:40 offset1:42
	v_add_f32_e32 v210, v25, v210
	v_add_f32_e32 v163, v26, v163
	v_add_f32_e32 v210, v27, v210
	v_exp_f32_e32 v28, v28
	s_waitcnt lgkmcnt(11)
	v_mfma_f32_32x32x16_bf16 v[80:95], v[220:223], v[96:99], v[164:179]
	ds_read2_b64 v[220:223], v244 offset0:12 offset1:14
	v_exp_f32_e32 v29, v29
	v_exp_f32_e32 v30, v30
	v_exp_f32_e32 v31, v31
	s_waitcnt lgkmcnt(11)
	v_mfma_f32_32x32x16_bf16 v[80:95], v[224:227], v[100:103], v[80:95]
	ds_read2_b64 v[224:227], v245 offset0:44 offset1:46
	v_add_f32_e32 v163, v28, v163
	v_add_f32_e32 v210, v29, v210
	v_add_f32_e32 v163, v30, v163
	v_add_f32_e32 v210, v31, v210
	s_waitcnt lgkmcnt(11)
	v_mfma_f32_32x32x16_bf16 v[80:95], v[228:231], v[104:107], v[80:95]
	v_cvt_pk_bf16_f32 v184, v24, v25
	v_cvt_pk_bf16_f32 v185, v26, v27
	v_cvt_pk_bf16_f32 v186, v28, v29
	v_cvt_pk_bf16_f32 v187, v30, v31
	v_exp_f32_e32 v64, v64
	s_waitcnt lgkmcnt(10)
	v_mfma_f32_32x32x16_bf16 v[80:95], v[232:235], v[108:111], v[80:95]
	v_exp_f32_e32 v65, v65
	v_exp_f32_e32 v66, v66
	s_waitcnt lgkmcnt(9)
	v_mfma_f32_32x32x16_bf16 v[80:95], v[236:239], v[112:115], v[80:95]
	v_exp_f32_e32 v67, v67
	v_add_f32_e32 v163, v64, v163
	v_add_f32_e32 v210, v65, v210
	s_waitcnt lgkmcnt(8)
	v_mfma_f32_32x32x16_bf16 v[80:95], v[240:243], v[116:119], v[80:95]
	v_add_f32_e32 v163, v66, v163
	v_add_f32_e32 v210, v67, v210
	v_exp_f32_e32 v68, v68
	v_exp_f32_e32 v69, v69
	s_waitcnt lgkmcnt(7)
	v_mfma_f32_32x32x16_bf16 v[32:47], v[132:135], v[180:183], v[32:47]
	v_exp_f32_e32 v70, v70
	v_exp_f32_e32 v71, v71
	s_waitcnt lgkmcnt(6)
	v_mfma_f32_32x32x16_bf16 v[0:15], v[136:139], v[180:183], v[0:15]
	v_add_f32_e32 v163, v68, v163
	v_add_f32_e32 v210, v69, v210
	v_add_f32_e32 v163, v70, v163
	v_add_f32_e32 v210, v71, v210
	v_cvt_pk_bf16_f32 v188, v64, v65
	s_waitcnt lgkmcnt(5)
	v_mfma_f32_32x32x16_bf16 v[32:47], v[198:201], v[184:187], v[32:47]
	v_cvt_pk_bf16_f32 v189, v66, v67
	v_cvt_pk_bf16_f32 v190, v68, v69
	v_cvt_pk_bf16_f32 v191, v70, v71
	v_exp_f32_e32 v72, v72
	s_waitcnt lgkmcnt(4)
	v_mfma_f32_32x32x16_bf16 v[0:15], v[202:205], v[184:187], v[0:15]
	v_exp_f32_e32 v73, v73
	v_exp_f32_e32 v74, v74
	v_exp_f32_e32 v75, v75
	s_waitcnt lgkmcnt(3)
	v_mfma_f32_32x32x16_bf16 v[32:47], v[248:251], v[188:191], v[32:47]
	v_add_f32_e32 v163, v72, v163
	v_add_f32_e32 v210, v73, v210
	v_add_f32_e32 v163, v74, v163
	v_add_f32_e32 v210, v75, v210
	s_waitcnt lgkmcnt(2)
	v_mfma_f32_32x32x16_bf16 v[0:15], v[216:219], v[188:191], v[0:15]
	v_exp_f32_e32 v76, v76
	v_exp_f32_e32 v77, v77
	v_exp_f32_e32 v78, v78
	v_exp_f32_e32 v79, v79
	v_add_f32_e32 v163, v76, v163
	v_add_f32_e32 v210, v77, v210
	v_add_f32_e32 v163, v78, v163
	v_add_f32_e32 v210, v79, v210
	v_cvt_pk_bf16_f32 v192, v72, v73
	v_cvt_pk_bf16_f32 v193, v74, v75
	v_cvt_pk_bf16_f32 v194, v76, v77
	v_cvt_pk_bf16_f32 v195, v78, v79
	s_waitcnt lgkmcnt(1)
	s_nop 0
	v_mfma_f32_32x32x16_bf16 v[32:47], v[220:223], v[192:195], v[32:47]
	s_waitcnt lgkmcnt(0)
	v_mfma_f32_32x32x16_bf16 v[0:15], v[224:227], v[192:195], v[0:15]
	v_add_f32_e32 v163, v163, v210
	v_add_f32_e32 v149, v149, v163
	v_cmp_lt_f32_e32 vcc, 0x45800000, v163
	s_cbranch_vccz .LBB0_566
; template <bool MLA, int DK, int DV>
; __device__ __forceinline__ void attn_core(const Params& p, int b, int h, int map, int q0, int nt, char* smem,
;                                           f32x16 (&o)[DV / 32], float& lout) {
;     ...
;     if (has1) {
;       mx *= sc;
;       if (__any(mx > mrun + 12.f)) {
;         mx = fmaxf(mx, __shfl_xor(mx, 32));
;         const float mnew = fmaxf(mrun, mx);
;         const float alpha = __builtin_amdgcn_exp2f(mrun - mnew);
;         mrun = mnew;
;         lrun *= alpha;
; #pragma unroll
;         for (int d = 0; d < NDVT; ++d)
; #pragma unroll
;           for (int i = 0; i < 16; ++i) o[d][i] *= alpha;
;       }
	v_max3_f32 v163, v16, v17, v18
	v_max3_f32 v163, v163, v19, v20
	v_max3_f32 v163, v163, v21, v22
	v_max3_f32 v163, v163, v23, v24
	v_max3_f32 v163, v163, v25, v26
	v_max3_f32 v163, v163, v27, v28
	v_max3_f32 v163, v163, v29, v30
	v_max3_f32 v163, v163, v31, v64
	v_max3_f32 v163, v163, v65, v66
	v_max3_f32 v163, v163, v67, v68
	v_max3_f32 v163, v163, v69, v70
	v_max3_f32 v163, v163, v71, v72
	v_max3_f32 v163, v163, v73, v74
	v_max3_f32 v163, v163, v75, v76
	v_max3_f32 v163, v163, v77, v78
	v_max_f32_e32 v163, v163, v79
	ds_bpermute_b32 v210, v156, v163
	s_waitcnt lgkmcnt(0)
	v_max_f32_e32 v163, v163, v210
	v_frexp_exp_i32_f32_e32 v210, v163
	v_max_i32_e32 v210, 0, v210
	v_sub_u32_e32 v247, 0, v210
	v_ldexp_f32 v247, 1.0, v247
	v_cvt_f32_i32_e32 v210, v210
	v_mul_f32_e32 v149, v149, v247
	v_mul_f32_e32 v32, v32, v247
	v_mul_f32_e32 v33, v33, v247
	v_mul_f32_e32 v34, v34, v247
	v_mul_f32_e32 v35, v35, v247
	v_mul_f32_e32 v36, v36, v247
	v_mul_f32_e32 v37, v37, v247
	v_mul_f32_e32 v38, v38, v247
	v_mul_f32_e32 v39, v39, v247
	v_mul_f32_e32 v40, v40, v247
	v_mul_f32_e32 v41, v41, v247
	v_mul_f32_e32 v42, v42, v247
	v_mul_f32_e32 v43, v43, v247
	v_mul_f32_e32 v44, v44, v247
	v_mul_f32_e32 v45, v45, v247
	v_mul_f32_e32 v46, v46, v247
	v_mul_f32_e32 v47, v47, v247
	v_mul_f32_e32 v0, v0, v247
	v_mul_f32_e32 v1, v1, v247
	v_mul_f32_e32 v2, v2, v247
	v_mul_f32_e32 v3, v3, v247
	v_mul_f32_e32 v4, v4, v247
	v_mul_f32_e32 v5, v5, v247
	v_mul_f32_e32 v6, v6, v247
	v_mul_f32_e32 v7, v7, v247
	v_mul_f32_e32 v8, v8, v247
	v_mul_f32_e32 v9, v9, v247
	v_mul_f32_e32 v10, v10, v247
	v_mul_f32_e32 v11, v11, v247
	v_mul_f32_e32 v12, v12, v247
	v_mul_f32_e32 v13, v13, v247
	v_mul_f32_e32 v14, v14, v247
	v_mul_f32_e32 v15, v15, v247
	v_sub_f32_e32 v164, v164, v210
	v_sub_f32_e32 v165, v165, v210
	v_sub_f32_e32 v166, v166, v210
	v_sub_f32_e32 v167, v167, v210
	v_sub_f32_e32 v168, v168, v210
	v_sub_f32_e32 v169, v169, v210
	v_sub_f32_e32 v170, v170, v210
	v_sub_f32_e32 v171, v171, v210
	v_sub_f32_e32 v172, v172, v210
	v_sub_f32_e32 v173, v173, v210
	v_sub_f32_e32 v174, v174, v210
	v_sub_f32_e32 v175, v175, v210
	v_sub_f32_e32 v176, v176, v210
	v_sub_f32_e32 v177, v177, v210
	v_sub_f32_e32 v178, v178, v210
	v_sub_f32_e32 v179, v179, v210
	v_sub_f32_e32 v48, v48, v210
	v_sub_f32_e32 v49, v49, v210
	v_sub_f32_e32 v50, v50, v210
	v_sub_f32_e32 v51, v51, v210
	v_sub_f32_e32 v52, v52, v210
	v_sub_f32_e32 v53, v53, v210
	v_sub_f32_e32 v54, v54, v210
	v_sub_f32_e32 v55, v55, v210
	v_sub_f32_e32 v56, v56, v210
	v_sub_f32_e32 v57, v57, v210
	v_sub_f32_e32 v58, v58, v210
	v_sub_f32_e32 v59, v59, v210
	v_sub_f32_e32 v60, v60, v210
	v_sub_f32_e32 v61, v61, v210
	v_sub_f32_e32 v62, v62, v210
	v_sub_f32_e32 v63, v63, v210
	v_sub_f32_e32 v80, v80, v210
	v_sub_f32_e32 v81, v81, v210
	v_sub_f32_e32 v82, v82, v210
	v_sub_f32_e32 v83, v83, v210
	v_sub_f32_e32 v84, v84, v210
	v_sub_f32_e32 v85, v85, v210
	v_sub_f32_e32 v86, v86, v210
	v_sub_f32_e32 v87, v87, v210
	v_sub_f32_e32 v88, v88, v210
	v_sub_f32_e32 v89, v89, v210
	v_sub_f32_e32 v90, v90, v210
	v_sub_f32_e32 v91, v91, v210
	v_sub_f32_e32 v92, v92, v210
	v_sub_f32_e32 v93, v93, v210
	v_sub_f32_e32 v94, v94, v210
	v_sub_f32_e32 v95, v95, v210
	v_add_f32_e32 v162, v162, v210
	s_branch .LBB0_566

; template <bool MLA, int DK, int DV>
; __device__ __forceinline__ void attn_core(const Params& p, int b, int h, int map, int q0, int nt, char* smem,
;                                           f32x16 (&o)[DV / 32], float& lout) {
;     ...
;     if (has2) ATTN_STOREK(kt & 1);
;     if (has1) ATTN_STOREV((kt + 1) & 1);
;     __syncthreads();
.LBB0_574:
	s_or_b64 exec, exec, s[74:75]
	s_cmp_lt_u32 s68, s34
	s_cselect_b64 s[72:73], -1, 0
	s_cmp_ge_u32 s68, s34
	s_waitcnt lgkmcnt(0)
	s_cbranch_scc1 .LBB0_588
	s_and_saveexec_b64 s[74:75], s[6:7]
	s_cbranch_execz .LBB0_581
	s_waitcnt vmcnt(0)
	v_add_u32_e32 v124, s38, v158
	v_add_u32_e32 v126, 0xc0, v124
	v_ashrrev_i32_e32 v127, 31, v126
	s_and_saveexec_b64 s[76:77], s[12:13]
	s_xor_b64 s[76:77], exec, s[76:77]
	v_lshlrev_b64 v[124:125], 6, v[126:127]
	s_movk_i32 s60, 0xff80
	v_lshl_add_u64 v[124:125], v[140:141], 0, v[124:125]
	s_mov_b32 s61, -1
	v_lshl_add_u64 v[124:125], v[124:125], 0, s[60:61]
	s_andn2_saveexec_b64 s[76:77], s[76:77]
	v_mad_i64_i32 v[124:125], s[80:81], v126, s1, v[142:143]
	s_or_b64 exec, exec, s[76:77]
	global_load_dwordx4 v[124:127], v[124:125], off
.LBB0_581:
	s_or_b64 exec, exec, s[74:75]
	s_and_saveexec_b64 s[74:75], s[8:9]
	s_cbranch_execz .LBB0_587
	v_add_u32_e32 v128, s38, v154
	v_add_u32_e32 v130, 0xc0, v128
	v_ashrrev_i32_e32 v131, 31, v130
	s_and_saveexec_b64 s[76:77], s[14:15]
	s_xor_b64 s[76:77], exec, s[76:77]
	v_lshlrev_b64 v[128:129], 6, v[130:131]
	s_movk_i32 s60, 0xff80
	v_lshl_add_u64 v[128:129], v[144:145], 0, v[128:129]
	s_mov_b32 s61, -1
	v_lshl_add_u64 v[128:129], v[128:129], 0, s[60:61]
	s_andn2_saveexec_b64 s[76:77], s[76:77]
	v_mad_i64_i32 v[128:129], s[80:81], v130, s1, v[146:147]
	s_or_b64 exec, exec, s[76:77]
	global_load_dwordx4 v[128:131], v[128:129], off

; template <bool MLA, int DK, int DV>
; __device__ __forceinline__ void attn_core(const Params& p, int b, int h, int map, int q0, int nt, char* smem,
;                                           f32x16 (&o)[DV / 32], float& lout) {
;     ...
;         for (int i = 0; i < 16; ++i) nxt_[sub][i] = 0.f;
;       constexpr int NM = 2 * NKS;
;       bf16x8 kf[NM];
; #pragma unroll
;       for (int j = 0; j < NM; ++j) kf[j] = *(const bf16x8*)(Kn + ((j / NKS) * 32 + r) * KS_STRIDE + (j % NKS) * 16 + h2 * 8);
; #pragma unroll
;       for (int j = 0; j < NM; ++j) {
;         nxt_[j / NKS] = MFMA32(kf[j], qf[j % NKS], nxt_[j / NKS]);
; #pragma unroll
;         for (int e_ = j * 32 / NM; e_ < (j + 1) * 32 / NM; ++e_) {
;           const float x_ = __builtin_amdgcn_exp2f(fmaf(cur_[e_ >> 4][e_ & 15], sc, -mrun));
;           cur_[e_ >> 4][e_ & 15] = x_; psum += x_;
;         }
;       }
;       __builtin_amdgcn_sched_group_barrier(0x100, NM, 0);
; #pragma unroll
;       for (int j = 0; j < NM; ++j) {
;         __builtin_amdgcn_sched_group_barrier(0x008, 1, 0);
;         __builtin_amdgcn_sched_group_barrier(0x002, 96 / NM, 0);
;       }
;     } else {
; #pragma unroll
;       for (int sub = 0; sub < 2; ++sub)
; #pragma unroll
;         for (int i = 0; i < 16; ++i) { const float x_ = __builtin_amdgcn_exp2f(fmaf(cur_[sub][i], sc, -mrun)); cur_[sub][i] = x_; psum += x_; }
;     }
;     lrun += psum;
;     bf16x8 pb[4];
; #pragma unroll
;     for (int kb = 0; kb < 4; ++kb) {
;       const int sub = kb >> 1, s8 = (kb & 1) * 8;
;       u32x4 pk;
;       pk.x = pack2(cur_[sub][s8 + 0], cur_[sub][s8 + 1]);
;       pk.y = pack2(cur_[sub][s8 + 2], cur_[sub][s8 + 3]);
;       pk.z = pack2(cur_[sub][s8 + 4], cur_[sub][s8 + 5]);
;       pk.w = pack2(cur_[sub][s8 + 6], cur_[sub][s8 + 7]);
;       pb[kb] = __builtin_bit_cast(bf16x8, pk);
;     }
;     float mx = -INFINITY;
; #pragma unroll
;     for (int hb = 0; hb < 2; ++hb) {
;       bf16x8 vf[2][NDVT];
; #pragma unroll
;       for (int q = 0; q < 2; ++q)
; #pragma unroll
;         for (int d = 0; d < NDVT; ++d) {
;           const bft* vp = Vc + (d * 32 + r) * VS_STRIDE + (hb * 2 + q) * 16 + 4 * h2;
;           const u32x2 lo = *(const u32x2*)vp, hi = *(const u32x2*)(vp + 8);
;           const u32x4 pa4 = {lo.x, lo.y, hi.x, hi.y};
;           vf[q][d] = __builtin_bit_cast(bf16x8, pa4);
;         }
; #pragma unroll
.LBB0_590:
	s_or_b64 exec, exec, s[74:75]
	s_barrier
	s_and_b64 vcc, exec, s[50:51]
	s_cbranch_vccnz .Lmla2_cold
	ds_read_b128 v[132:135], v155 offset:0
	ds_read_b128 v[136:139], v155 offset:32
	ds_read_b128 v[198:201], v155 offset:64
	ds_read_b128 v[202:205], v155 offset:96
	ds_read_b128 v[248:251], v155 offset:128
	ds_read_b128 v[216:219], v155 offset:160
	ds_read_b128 v[220:223], v155 offset:6656
	ds_read_b128 v[224:227], v155 offset:6688
	ds_read_b128 v[228:231], v155 offset:6720
	ds_read_b128 v[232:235], v155 offset:6752
	ds_read_b128 v[236:239], v155 offset:6784
	ds_read_b128 v[240:243], v155 offset:6816
	v_add_u32_e32 v244, 0x8800, v157
	v_add_u32_e32 v245, 0x9800, v157
	v_exp_f32_e32 v48, v48
	v_exp_f32_e32 v49, v49
	v_exp_f32_e32 v50, v50
	v_exp_f32_e32 v51, v51
	v_add_f32_e32 v163, v48, v50
	v_add_f32_e32 v210, v49, v51
	s_waitcnt lgkmcnt(11)
	v_mfma_f32_32x32x16_bf16 v[16:31], v[132:135], v[96:99], v[164:179]
	v_exp_f32_e32 v52, v52
	v_exp_f32_e32 v53, v53
	v_exp_f32_e32 v54, v54
	s_waitcnt lgkmcnt(10)
	v_mfma_f32_32x32x16_bf16 v[16:31], v[136:139], v[100:103], v[16:31]
	v_exp_f32_e32 v55, v55
	v_add_f32_e32 v163, v52, v163
	v_add_f32_e32 v210, v53, v210
	s_waitcnt lgkmcnt(9)
	v_mfma_f32_32x32x16_bf16 v[16:31], v[198:201], v[104:107], v[16:31]
	v_add_f32_e32 v163, v54, v163
	v_add_f32_e32 v210, v55, v210
	v_cvt_pk_bf16_f32 v180, v48, v49
	v_cvt_pk_bf16_f32 v181, v50, v51
	v_cvt_pk_bf16_f32 v182, v52, v53
	s_waitcnt lgkmcnt(8)
	v_mfma_f32_32x32x16_bf16 v[16:31], v[202:205], v[108:111], v[16:31]
	v_cvt_pk_bf16_f32 v183, v54, v55
	v_exp_f32_e32 v56, v56
	v_exp_f32_e32 v57, v57
	s_waitcnt lgkmcnt(7)
	v_mfma_f32_32x32x16_bf16 v[16:31], v[248:251], v[112:115], v[16:31]
	v_exp_f32_e32 v58, v58
	v_exp_f32_e32 v59, v59
	v_add_f32_e32 v163, v56, v163
	s_waitcnt lgkmcnt(6)
	v_mfma_f32_32x32x16_bf16 v[16:31], v[216:219], v[116:119], v[16:31]
	ds_read2_b64 v[132:135], v244 offset0:64 offset1:66
	ds_read2_b64 v[136:139], v245 offset0:96 offset1:98
	ds_read2_b64 v[198:201], v244 offset0:68 offset1:70
	ds_read2_b64 v[202:205], v245 offset0:100 offset1:102
	ds_read2_b64 v[248:251], v244 offset0:72 offset1:74
	ds_read2_b64 v[216:219], v245 offset0:104 offset1:106
	v_add_f32_e32 v210, v57, v210
	v_add_f32_e32 v163, v58, v163
	v_add_f32_e32 v210, v59, v210
	v_exp_f32_e32 v60, v60
	s_waitcnt lgkmcnt(11)
	v_mfma_f32_32x32x16_bf16 v[64:79], v[220:223], v[96:99], v[164:179]
	ds_read2_b64 v[220:223], v244 offset0:76 offset1:78
	v_exp_f32_e32 v61, v61
	v_exp_f32_e32 v62, v62
	v_exp_f32_e32 v63, v63
	s_waitcnt lgkmcnt(11)
	v_mfma_f32_32x32x16_bf16 v[64:79], v[224:227], v[100:103], v[64:79]
	ds_read2_b64 v[224:227], v245 offset0:108 offset1:110
	v_add_f32_e32 v163, v60, v163
	v_add_f32_e32 v210, v61, v210
	v_add_f32_e32 v163, v62, v163
	v_add_f32_e32 v210, v63, v210
	s_waitcnt lgkmcnt(11)
	v_mfma_f32_32x32x16_bf16 v[64:79], v[228:231], v[104:107], v[64:79]
	v_cvt_pk_bf16_f32 v184, v56, v57
	v_cvt_pk_bf16_f32 v185, v58, v59
	v_cvt_pk_bf16_f32 v186, v60, v61
	v_cvt_pk_bf16_f32 v187, v62, v63
	v_exp_f32_e32 v80, v80
	s_waitcnt lgkmcnt(10)
	v_mfma_f32_32x32x16_bf16 v[64:79], v[232:235], v[108:111], v[64:79]
	v_exp_f32_e32 v81, v81
	v_exp_f32_e32 v82, v82
	s_waitcnt lgkmcnt(9)
	v_mfma_f32_32x32x16_bf16 v[64:79], v[236:239], v[112:115], v[64:79]
	v_exp_f32_e32 v83, v83
	v_add_f32_e32 v163, v80, v163
	v_add_f32_e32 v210, v81, v210
	s_waitcnt lgkmcnt(8)
	v_mfma_f32_32x32x16_bf16 v[64:79], v[240:243], v[116:119], v[64:79]
	v_add_f32_e32 v163, v82, v163
	v_add_f32_e32 v210, v83, v210
	v_exp_f32_e32 v84, v84
	v_exp_f32_e32 v85, v85
	s_waitcnt lgkmcnt(7)
	v_mfma_f32_32x32x16_bf16 v[32:47], v[132:135], v[180:183], v[32:47]
	v_exp_f32_e32 v86, v86
	v_exp_f32_e32 v87, v87
	s_waitcnt lgkmcnt(6)
	v_mfma_f32_32x32x16_bf16 v[0:15], v[136:139], v[180:183], v[0:15]
	v_add_f32_e32 v163, v84, v163
	v_add_f32_e32 v210, v85, v210
	v_add_f32_e32 v163, v86, v163
	v_add_f32_e32 v210, v87, v210
	v_cvt_pk_bf16_f32 v188, v80, v81
	s_waitcnt lgkmcnt(5)
	v_mfma_f32_32x32x16_bf16 v[32:47], v[198:201], v[184:187], v[32:47]
	v_cvt_pk_bf16_f32 v189, v82, v83
	v_cvt_pk_bf16_f32 v190, v84, v85
	v_cvt_pk_bf16_f32 v191, v86, v87
	v_exp_f32_e32 v88, v88
	s_waitcnt lgkmcnt(4)
	v_mfma_f32_32x32x16_bf16 v[0:15], v[202:205], v[184:187], v[0:15]
	v_exp_f32_e32 v89, v89
	v_exp_f32_e32 v90, v90
	v_exp_f32_e32 v91, v91
	s_waitcnt lgkmcnt(3)
	v_mfma_f32_32x32x16_bf16 v[32:47], v[248:251], v[188:191], v[32:47]
	v_add_f32_e32 v163, v88, v163
	v_add_f32_e32 v210, v89, v210
	v_add_f32_e32 v163, v90, v163
	v_add_f32_e32 v210, v91, v210
	s_waitcnt lgkmcnt(2)
	v_mfma_f32_32x32x16_bf16 v[0:15], v[216:219], v[188:191], v[0:15]
	v_exp_f32_e32 v92, v92
	v_exp_f32_e32 v93, v93
	v_exp_f32_e32 v94, v94
	v_exp_f32_e32 v95, v95
	v_add_f32_e32 v163, v92, v163
	v_add_f32_e32 v210, v93, v210
	v_add_f32_e32 v163, v94, v163
	v_add_f32_e32 v210, v95, v210
	v_cvt_pk_bf16_f32 v192, v88, v89
	v_cvt_pk_bf16_f32 v193, v90, v91
	v_cvt_pk_bf16_f32 v194, v92, v93
	v_cvt_pk_bf16_f32 v195, v94, v95
	s_waitcnt lgkmcnt(1)
	s_nop 0
	v_mfma_f32_32x32x16_bf16 v[32:47], v[220:223], v[192:195], v[32:47]
	s_waitcnt lgkmcnt(0)
	v_mfma_f32_32x32x16_bf16 v[0:15], v[224:227], v[192:195], v[0:15]
	v_add_f32_e32 v163, v163, v210
	v_add_f32_e32 v149, v149, v163
	v_cmp_lt_f32_e32 vcc, 0x45800000, v163
	s_cbranch_vccz .LBB0_597
; template <bool MLA, int DK, int DV>
; __device__ __forceinline__ void attn_core(const Params& p, int b, int h, int map, int q0, int nt, char* smem,
;                                           f32x16 (&o)[DV / 32], float& lout) {
;     ...
;     if (has1) {
;       mx *= sc;
;       if (__any(mx > mrun + 12.f)) {
;         mx = fmaxf(mx, __shfl_xor(mx, 32));
;         const float mnew = fmaxf(mrun, mx);
;         const float alpha = __builtin_amdgcn_exp2f(mrun - mnew);
;         mrun = mnew;
;         lrun *= alpha;
; #pragma unroll
;         for (int d = 0; d < NDVT; ++d)
; #pragma unroll
;           for (int i = 0; i < 16; ++i) o[d][i] *= alpha;
;       }
	v_max3_f32 v163, v48, v49, v50
	v_max3_f32 v163, v163, v51, v52
	v_max3_f32 v163, v163, v53, v54
	v_max3_f32 v163, v163, v55, v56
	v_max3_f32 v163, v163, v57, v58
	v_max3_f32 v163, v163, v59, v60
	v_max3_f32 v163, v163, v61, v62
	v_max3_f32 v163, v163, v63, v80
	v_max3_f32 v163, v163, v81, v82
	v_max3_f32 v163, v163, v83, v84
	v_max3_f32 v163, v163, v85, v86
	v_max3_f32 v163, v163, v87, v88
	v_max3_f32 v163, v163, v89, v90
	v_max3_f32 v163, v163, v91, v92
	v_max3_f32 v163, v163, v93, v94
	v_max_f32_e32 v163, v163, v95
	ds_bpermute_b32 v210, v156, v163
	s_waitcnt lgkmcnt(0)
	v_max_f32_e32 v163, v163, v210
	v_frexp_exp_i32_f32_e32 v210, v163
	v_max_i32_e32 v210, 0, v210
	v_sub_u32_e32 v247, 0, v210
	v_ldexp_f32 v247, 1.0, v247
	v_cvt_f32_i32_e32 v210, v210
	v_mul_f32_e32 v149, v149, v247
	v_mul_f32_e32 v32, v32, v247
	v_mul_f32_e32 v33, v33, v247
	v_mul_f32_e32 v34, v34, v247
	v_mul_f32_e32 v35, v35, v247
	v_mul_f32_e32 v36, v36, v247
	v_mul_f32_e32 v37, v37, v247
	v_mul_f32_e32 v38, v38, v247
	v_mul_f32_e32 v39, v39, v247
	v_mul_f32_e32 v40, v40, v247
	v_mul_f32_e32 v41, v41, v247
	v_mul_f32_e32 v42, v42, v247
	v_mul_f32_e32 v43, v43, v247
	v_mul_f32_e32 v44, v44, v247
	v_mul_f32_e32 v45, v45, v247
	v_mul_f32_e32 v46, v46, v247
	v_mul_f32_e32 v47, v47, v247
	v_mul_f32_e32 v0, v0, v247
	v_mul_f32_e32 v1, v1, v247
	v_mul_f32_e32 v2, v2, v247
	v_mul_f32_e32 v3, v3, v247
	v_mul_f32_e32 v4, v4, v247
	v_mul_f32_e32 v5, v5, v247
	v_mul_f32_e32 v6, v6, v247
	v_mul_f32_e32 v7, v7, v247
	v_mul_f32_e32 v8, v8, v247
	v_mul_f32_e32 v9, v9, v247
	v_mul_f32_e32 v10, v10, v247
	v_mul_f32_e32 v11, v11, v247
	v_mul_f32_e32 v12, v12, v247
	v_mul_f32_e32 v13, v13, v247
	v_mul_f32_e32 v14, v14, v247
	v_mul_f32_e32 v15, v15, v247
	v_sub_f32_e32 v164, v164, v210
	v_sub_f32_e32 v165, v165, v210
	v_sub_f32_e32 v166, v166, v210
	v_sub_f32_e32 v167, v167, v210
	v_sub_f32_e32 v168, v168, v210
	v_sub_f32_e32 v169, v169, v210
	v_sub_f32_e32 v170, v170, v210
	v_sub_f32_e32 v171, v171, v210
	v_sub_f32_e32 v172, v172, v210
	v_sub_f32_e32 v173, v173, v210
	v_sub_f32_e32 v174, v174, v210
	v_sub_f32_e32 v175, v175, v210
	v_sub_f32_e32 v176, v176, v210
	v_sub_f32_e32 v177, v177, v210
	v_sub_f32_e32 v178, v178, v210
	v_sub_f32_e32 v179, v179, v210
	v_sub_f32_e32 v16, v16, v210
	v_sub_f32_e32 v17, v17, v210
	v_sub_f32_e32 v18, v18, v210
	v_sub_f32_e32 v19, v19, v210
	v_sub_f32_e32 v20, v20, v210
	v_sub_f32_e32 v21, v21, v210
	v_sub_f32_e32 v22, v22, v210
	v_sub_f32_e32 v23, v23, v210
	v_sub_f32_e32 v24, v24, v210
	v_sub_f32_e32 v25, v25, v210
	v_sub_f32_e32 v26, v26, v210
	v_sub_f32_e32 v27, v27, v210
	v_sub_f32_e32 v28, v28, v210
	v_sub_f32_e32 v29, v29, v210
	v_sub_f32_e32 v30, v30, v210
	v_sub_f32_e32 v31, v31, v210
	v_sub_f32_e32 v64, v64, v210
	v_sub_f32_e32 v65, v65, v210
	v_sub_f32_e32 v66, v66, v210
	v_sub_f32_e32 v67, v67, v210
	v_sub_f32_e32 v68, v68, v210
	v_sub_f32_e32 v69, v69, v210
	v_sub_f32_e32 v70, v70, v210
	v_sub_f32_e32 v71, v71, v210
	v_sub_f32_e32 v72, v72, v210
	v_sub_f32_e32 v73, v73, v210
	v_sub_f32_e32 v74, v74, v210
	v_sub_f32_e32 v75, v75, v210
	v_sub_f32_e32 v76, v76, v210
	v_sub_f32_e32 v77, v77, v210
	v_sub_f32_e32 v78, v78, v210
	v_sub_f32_e32 v79, v79, v210
	v_add_f32_e32 v162, v162, v210
	s_branch .LBB0_597

; DI unsigned pack2(float lo, float hi) { f2v_ f = {lo, hi}; b2v_ b = __builtin_convertvector(f, b2v_); return __builtin_bit_cast(unsigned, b); }
; DI int otid() { int t = threadIdx.x; asm volatile("" : "+v"(t)); return t; }
; template <bool MLA, int DK, int DV>
; __device__ __forceinline__ void attn_core(const Params& p, int b, int h, int map, int q0, int nt, char* smem,
;                                           f32x16 (&o)[DV / 32], float& lout) {
;     ...
;   lout = lrun + __shfl_xor(lrun, 32);
; }
; __device__ __forceinline__ void mla_item(const Params& p, int b, int h, int qb, char* smem) {
;   const int lane = otid() & 63, wave = otid() >> 6, r = lane & 31, h2 = lane >> 5;
;   const int q0 = qb * 256;
;   const int nt = ((q0 < CTXL) ? CTXL : NTOK) / 64;
;   f32x16 o[2];
;   float l;
;   attn_core<true, 96, 64>(p, b, h, 0, q0, nt, smem, o, l);
;   bft* O = (bft*)(p.ws + OFF_XN);
;   const int orow = b * NTOK + q0 + wave * 32 + r;
;   const float inv = 1.f / l;
; #pragma unroll
;   for (int d = 0; d < 2; ++d)
; #pragma unroll
;     for (int i4 = 0; i4 < 4; ++i4) {
;       const int dv = d * 32 + 8 * i4 + 4 * h2;
;       u32x2 w;
;       w.x = pack2(o[d][i4 * 4 + 0] * inv, o[d][i4 * 4 + 1] * inv);
;       w.y = pack2(o[d][i4 * 4 + 2] * inv, o[d][i4 * 4 + 3] * inv);
;       *(u32x2*)(O + (size_t)orow * D + h * 64 + dv) = w;
;     }
.LBB0_605:
	s_barrier
	ds_bpermute_b32 v16, v156, v149
	v_ashrrev_i32_e32 v17, 1, v153
	v_and_b32_e32 v17, 0xffffffe0, v17
	v_add_u32_e32 v17, s86, v17
	s_lshl_b32 s52, s49, 1
	s_waitcnt lgkmcnt(0)
	v_add_f32_e32 v18, v149, v16
	v_div_scale_f32 v19, s[6:7], v18, v18, 1.0
	v_rcp_f32_e32 v20, v19
	v_and_or_b32 v16, v152, 31, v17
	v_div_scale_f32 v17, vcc, 1.0, v18, 1.0
	v_fma_f32 v21, -v19, v20, 1.0
	v_fmac_f32_e32 v20, v21, v20
	v_mul_f32_e32 v21, v17, v20
	v_fma_f32 v22, -v19, v21, v17
	v_fmac_f32_e32 v21, v22, v20
	v_fma_f32 v17, -v19, v21, v17
	v_div_fmas_f32 v17, v17, v20, v21
	v_div_fixup_f32 v18, v17, v18, 1.0
	v_ashrrev_i32_e32 v17, 31, v16
	v_lshlrev_b64 v[16:17], 11, v[16:17]
	v_lshl_add_u64 v[16:17], s[62:63], 0, v[16:17]
	v_pk_mul_f32 v[20:21], v[32:33], v[18:19] op_sel_hi:[1,0]
	v_pk_mul_f32 v[22:23], v[34:35], v[18:19] op_sel_hi:[1,0]
	v_lshrrev_b32_e32 v19, 2, v152
	v_lshl_add_u64 v[16:17], v[16:17], 0, s[52:53]
	v_and_b32_e32 v160, 8, v19
	v_pk_mul_f32 v[0:1], v[0:1], v[18:19] op_sel_hi:[1,0]
	v_pk_mul_f32 v[2:3], v[2:3], v[18:19] op_sel_hi:[1,0]
	v_cvt_pk_bf16_f32 v20, v20, v21
	v_cvt_pk_bf16_f32 v21, v22, v23
	v_lshl_add_u64 v[16:17], v[16:17], 0, v[160:161]
	v_cvt_pk_bf16_f32 v0, v0, v1
	v_cvt_pk_bf16_f32 v1, v2, v3
	global_store_dwordx2 v[16:17], v[20:21], off
	v_pk_mul_f32 v[20:21], v[36:37], v[18:19] op_sel_hi:[1,0]
	v_pk_mul_f32 v[22:23], v[38:39], v[18:19] op_sel_hi:[1,0]
	global_store_dwordx2 v[16:17], v[0:1], off offset:64
	v_pk_mul_f32 v[0:1], v[4:5], v[18:19] op_sel_hi:[1,0]
	v_pk_mul_f32 v[2:3], v[6:7], v[18:19] op_sel_hi:[1,0]
	v_cvt_pk_bf16_f32 v20, v20, v21
	v_cvt_pk_bf16_f32 v21, v22, v23
	v_cvt_pk_bf16_f32 v0, v0, v1
	v_cvt_pk_bf16_f32 v1, v2, v3
	global_store_dwordx2 v[16:17], v[20:21], off offset:16
	v_pk_mul_f32 v[20:21], v[40:41], v[18:19] op_sel_hi:[1,0]
	v_pk_mul_f32 v[22:23], v[42:43], v[18:19] op_sel_hi:[1,0]
	global_store_dwordx2 v[16:17], v[0:1], off offset:80
	v_pk_mul_f32 v[0:1], v[8:9], v[18:19] op_sel_hi:[1,0]
	v_pk_mul_f32 v[2:3], v[10:11], v[18:19] op_sel_hi:[1,0]
	v_cvt_pk_bf16_f32 v20, v20, v21
	v_cvt_pk_bf16_f32 v21, v22, v23
	v_cvt_pk_bf16_f32 v0, v0, v1
	v_cvt_pk_bf16_f32 v1, v2, v3
	global_store_dwordx2 v[16:17], v[20:21], off offset:32
	v_pk_mul_f32 v[20:21], v[44:45], v[18:19] op_sel_hi:[1,0]
	v_pk_mul_f32 v[22:23], v[46:47], v[18:19] op_sel_hi:[1,0]
	global_store_dwordx2 v[16:17], v[0:1], off offset:96
	v_pk_mul_f32 v[0:1], v[12:13], v[18:19] op_sel_hi:[1,0]
	v_pk_mul_f32 v[2:3], v[14:15], v[18:19] op_sel_hi:[1,0]
	s_mov_b32 s65, s53
	s_mov_b32 s52, 0x800000
	v_cvt_pk_bf16_f32 v20, v20, v21
	v_cvt_pk_bf16_f32 v21, v22, v23
	v_cvt_pk_bf16_f32 v0, v0, v1
	v_cvt_pk_bf16_f32 v1, v2, v3
	s_mov_b64 s[8:9], 0
	global_store_dwordx2 v[16:17], v[20:21], off offset:48
	global_store_dwordx2 v[16:17], v[0:1], off offset:112
